# row-pass sample-row split-K slab sums de-serialized: batched global loads (24/20 or 16 in flight, one wait per batch), same summation order
# speedup vs baseline: 1.8382x; 1.0167x over previous
; DI void rowpass(const Params& p, bool init, float scale, const float* __restrict__ gpost, const float* __restrict__ gnext, int nparts, int bid, int nb, const int tid) {
;     ...
;             float4 y[4];
;             float ss = 0.f;
; #pragma unroll
;             for (int i = 0; i < 4; ++i) h[i] = *(const float4*)(H + (size_t)row * DM + i * 256 + lane * 4);
;             if (row < NP) {
;                 u32x2 yb[4];
; #pragma unroll
;                 for (int i = 0; i < 4; ++i) yb[i] = *(const u32x2*)(YB + (size_t)row * DM + i * 256 + lane * 4);
; #pragma unroll
;                 for (int i = 0; i < 4; ++i) y[i] = make_float4(__uint_as_float(yb[i].x << 16), __uint_as_float(yb[i].x & 0xffff0000u), __uint_as_float(yb[i].y << 16), __uint_as_float(yb[i].y & 0xffff0000u));
;             } else {
; #pragma unroll
;                 for (int i = 0; i < 4; ++i) y[i] = make_float4(0.f, 0.f, 0.f, 0.f);
;                 for (int pt = 0; pt < nparts; ++pt) {
; #pragma unroll
;                     for (int i = 0; i < 4; ++i) { const float4 u = *(const float4*)(YS + (size_t)pt * NS * DM + (size_t)(row - NP) * DM + i * 256 + lane * 4); y[i].x += u.x; y[i].y += u.y; y[i].z += u.z; y[i].w += u.w; }
;                 }
.LBB0_153:
	flat_load_dwordx4 v[36:39], v[48:49]
	flat_load_dwordx4 v[32:35], v[48:49] offset:1024
	flat_load_dwordx4 v[28:31], v[48:49] offset:2048
	flat_load_dwordx4 v[24:27], v[48:49] offset:3072
	s_cmpk_gt_i32 s2, 0x3fff
	s_mov_b64 s[0:1], -1
	s_cbranch_scc0 .LBB0_155
	s_add_i32 s86, s2, 0xffffc000
	s_lshl_b64 s[0:1], s[86:87], 12
	v_lshl_add_u64 v[40:41], v[18:19], 0, s[0:1]
	global_load_dwordx4 v[84:87], v[40:41], off
	global_load_dwordx4 v[88:91], v[40:41], off offset:1024
	global_load_dwordx4 v[92:95], v[40:41], off offset:2048
	global_load_dwordx4 v[96:99], v[40:41], off offset:3072
	v_add_co_u32_e32 v200, vcc, 0x100000, v40
	s_nop 1
	v_addc_co_u32_e32 v201, vcc, 0, v41, vcc
	global_load_dwordx4 v[100:103], v[200:201], off
	global_load_dwordx4 v[104:107], v[200:201], off offset:1024
	global_load_dwordx4 v[108:111], v[200:201], off offset:2048
	global_load_dwordx4 v[112:115], v[200:201], off offset:3072
	v_add_co_u32_e32 v200, vcc, 0x200000, v40
	s_nop 1
	v_addc_co_u32_e32 v201, vcc, 0, v41, vcc
	global_load_dwordx4 v[116:119], v[200:201], off
	global_load_dwordx4 v[120:123], v[200:201], off offset:1024
	global_load_dwordx4 v[124:127], v[200:201], off offset:2048
	global_load_dwordx4 v[128:131], v[200:201], off offset:3072
	v_add_co_u32_e32 v200, vcc, 0x300000, v40
	s_nop 1
	v_addc_co_u32_e32 v201, vcc, 0, v41, vcc
	global_load_dwordx4 v[132:135], v[200:201], off
	global_load_dwordx4 v[136:139], v[200:201], off offset:1024
	global_load_dwordx4 v[140:143], v[200:201], off offset:2048
	global_load_dwordx4 v[144:147], v[200:201], off offset:3072
	v_add_co_u32_e32 v200, vcc, 0x400000, v40
	s_nop 1
	v_addc_co_u32_e32 v201, vcc, 0, v41, vcc
	global_load_dwordx4 v[148:151], v[200:201], off
	global_load_dwordx4 v[152:155], v[200:201], off offset:1024
	global_load_dwordx4 v[156:159], v[200:201], off offset:2048
	global_load_dwordx4 v[160:163], v[200:201], off offset:3072
	v_add_co_u32_e32 v200, vcc, 0x500000, v40
	s_nop 1
	v_addc_co_u32_e32 v201, vcc, 0, v41, vcc
	global_load_dwordx4 v[164:167], v[200:201], off
	global_load_dwordx4 v[168:171], v[200:201], off offset:1024
	global_load_dwordx4 v[172:175], v[200:201], off offset:2048
	global_load_dwordx4 v[176:179], v[200:201], off offset:3072
	s_waitcnt vmcnt(0) lgkmcnt(0)
; DI void rowpass(const Params& p, bool init, float scale, const float* __restrict__ gpost, const float* __restrict__ gnext, int nparts, int bid, int nb, const int tid) {
;     ...
;                 for (int pt = 0; pt < nparts; ++pt) {
; #pragma unroll
;                     for (int i = 0; i < 4; ++i) { const float4 u = *(const float4*)(YS + (size_t)pt * NS * DM + (size_t)(row - NP) * DM + i * 256 + lane * 4); y[i].x += u.x; y[i].y += u.y; y[i].z += u.z; y[i].w += u.w; }
;                 }
	v_pk_add_f32 v[180:181], v[84:85], 0 op_sel_hi:[1,0]
	v_pk_add_f32 v[182:183], v[86:87], 0 op_sel_hi:[1,0]
	v_pk_add_f32 v[184:185], v[88:89], 0 op_sel_hi:[1,0]
	v_pk_add_f32 v[186:187], v[90:91], 0 op_sel_hi:[1,0]
	v_pk_add_f32 v[188:189], v[92:93], 0 op_sel_hi:[1,0]
	v_pk_add_f32 v[190:191], v[94:95], 0 op_sel_hi:[1,0]
	v_pk_add_f32 v[196:197], v[96:97], 0 op_sel_hi:[1,0]
	v_pk_add_f32 v[198:199], v[98:99], 0 op_sel_hi:[1,0]
	v_pk_add_f32 v[180:181], v[180:181], v[100:101]
	v_pk_add_f32 v[182:183], v[182:183], v[102:103]
	v_pk_add_f32 v[184:185], v[184:185], v[104:105]
	v_pk_add_f32 v[186:187], v[186:187], v[106:107]
	v_pk_add_f32 v[188:189], v[188:189], v[108:109]
	v_pk_add_f32 v[190:191], v[190:191], v[110:111]
	v_pk_add_f32 v[196:197], v[196:197], v[112:113]
	v_pk_add_f32 v[198:199], v[198:199], v[114:115]
	v_pk_add_f32 v[180:181], v[180:181], v[116:117]
	v_pk_add_f32 v[182:183], v[182:183], v[118:119]
	v_pk_add_f32 v[184:185], v[184:185], v[120:121]
	v_pk_add_f32 v[186:187], v[186:187], v[122:123]
	v_pk_add_f32 v[188:189], v[188:189], v[124:125]
	v_pk_add_f32 v[190:191], v[190:191], v[126:127]
	v_pk_add_f32 v[196:197], v[196:197], v[128:129]
	v_pk_add_f32 v[198:199], v[198:199], v[130:131]
	v_pk_add_f32 v[180:181], v[180:181], v[132:133]
	v_pk_add_f32 v[182:183], v[182:183], v[134:135]
	v_pk_add_f32 v[184:185], v[184:185], v[136:137]
	v_pk_add_f32 v[186:187], v[186:187], v[138:139]
	v_pk_add_f32 v[188:189], v[188:189], v[140:141]
	v_pk_add_f32 v[190:191], v[190:191], v[142:143]
	v_pk_add_f32 v[196:197], v[196:197], v[144:145]
	v_pk_add_f32 v[198:199], v[198:199], v[146:147]
	v_pk_add_f32 v[180:181], v[180:181], v[148:149]
	v_pk_add_f32 v[182:183], v[182:183], v[150:151]
	v_pk_add_f32 v[184:185], v[184:185], v[152:153]
	v_pk_add_f32 v[186:187], v[186:187], v[154:155]
	v_pk_add_f32 v[188:189], v[188:189], v[156:157]
	v_pk_add_f32 v[190:191], v[190:191], v[158:159]
	v_pk_add_f32 v[196:197], v[196:197], v[160:161]
	v_pk_add_f32 v[198:199], v[198:199], v[162:163]
	v_pk_add_f32 v[180:181], v[180:181], v[164:165]
	v_pk_add_f32 v[182:183], v[182:183], v[166:167]
	v_pk_add_f32 v[184:185], v[184:185], v[168:169]
	v_pk_add_f32 v[186:187], v[186:187], v[170:171]
	v_pk_add_f32 v[188:189], v[188:189], v[172:173]
	v_pk_add_f32 v[190:191], v[190:191], v[174:175]
	v_pk_add_f32 v[196:197], v[196:197], v[176:177]
	v_pk_add_f32 v[198:199], v[198:199], v[178:179]
	v_add_co_u32_e32 v200, vcc, 0x600000, v40
	s_nop 1
	v_addc_co_u32_e32 v201, vcc, 0, v41, vcc
	global_load_dwordx4 v[84:87], v[200:201], off
	global_load_dwordx4 v[88:91], v[200:201], off offset:1024
	global_load_dwordx4 v[92:95], v[200:201], off offset:2048
	global_load_dwordx4 v[96:99], v[200:201], off offset:3072
	v_add_co_u32_e32 v200, vcc, 0x700000, v40
	s_nop 1
	v_addc_co_u32_e32 v201, vcc, 0, v41, vcc
	global_load_dwordx4 v[100:103], v[200:201], off
	global_load_dwordx4 v[104:107], v[200:201], off offset:1024
	global_load_dwordx4 v[108:111], v[200:201], off offset:2048
	global_load_dwordx4 v[112:115], v[200:201], off offset:3072
	v_add_co_u32_e32 v200, vcc, 0x800000, v40
	s_nop 1
	v_addc_co_u32_e32 v201, vcc, 0, v41, vcc
	global_load_dwordx4 v[116:119], v[200:201], off
	global_load_dwordx4 v[120:123], v[200:201], off offset:1024
	global_load_dwordx4 v[124:127], v[200:201], off offset:2048
	global_load_dwordx4 v[128:131], v[200:201], off offset:3072
	v_add_co_u32_e32 v200, vcc, 0x900000, v40
	s_nop 1
	v_addc_co_u32_e32 v201, vcc, 0, v41, vcc
	global_load_dwordx4 v[132:135], v[200:201], off
	global_load_dwordx4 v[136:139], v[200:201], off offset:1024
	global_load_dwordx4 v[140:143], v[200:201], off offset:2048
	global_load_dwordx4 v[144:147], v[200:201], off offset:3072
	v_add_co_u32_e32 v200, vcc, 0xa00000, v40
	s_nop 1
	v_addc_co_u32_e32 v201, vcc, 0, v41, vcc
	global_load_dwordx4 v[148:151], v[200:201], off
	global_load_dwordx4 v[152:155], v[200:201], off offset:1024
	global_load_dwordx4 v[156:159], v[200:201], off offset:2048
	global_load_dwordx4 v[160:163], v[200:201], off offset:3072
	s_waitcnt vmcnt(0) lgkmcnt(0)
	v_pk_add_f32 v[180:181], v[180:181], v[84:85]
	v_pk_add_f32 v[182:183], v[182:183], v[86:87]
	v_pk_add_f32 v[184:185], v[184:185], v[88:89]
	v_pk_add_f32 v[186:187], v[186:187], v[90:91]
	v_pk_add_f32 v[188:189], v[188:189], v[92:93]
	v_pk_add_f32 v[190:191], v[190:191], v[94:95]
	v_pk_add_f32 v[196:197], v[196:197], v[96:97]
	v_pk_add_f32 v[198:199], v[198:199], v[98:99]
	v_pk_add_f32 v[180:181], v[180:181], v[100:101]
	v_pk_add_f32 v[182:183], v[182:183], v[102:103]
	v_pk_add_f32 v[184:185], v[184:185], v[104:105]
	v_pk_add_f32 v[186:187], v[186:187], v[106:107]
	v_pk_add_f32 v[188:189], v[188:189], v[108:109]
	v_pk_add_f32 v[190:191], v[190:191], v[110:111]
	v_pk_add_f32 v[196:197], v[196:197], v[112:113]
	v_pk_add_f32 v[198:199], v[198:199], v[114:115]
	v_pk_add_f32 v[180:181], v[180:181], v[116:117]
	v_pk_add_f32 v[182:183], v[182:183], v[118:119]
	v_pk_add_f32 v[184:185], v[184:185], v[120:121]
	v_pk_add_f32 v[186:187], v[186:187], v[122:123]
	v_pk_add_f32 v[188:189], v[188:189], v[124:125]
	v_pk_add_f32 v[190:191], v[190:191], v[126:127]
	v_pk_add_f32 v[196:197], v[196:197], v[128:129]
	v_pk_add_f32 v[198:199], v[198:199], v[130:131]
	v_pk_add_f32 v[180:181], v[180:181], v[132:133]
	v_pk_add_f32 v[182:183], v[182:183], v[134:135]
	v_pk_add_f32 v[184:185], v[184:185], v[136:137]
	v_pk_add_f32 v[186:187], v[186:187], v[138:139]
	v_pk_add_f32 v[188:189], v[188:189], v[140:141]
	v_pk_add_f32 v[190:191], v[190:191], v[142:143]
	v_pk_add_f32 v[196:197], v[196:197], v[144:145]
	v_pk_add_f32 v[198:199], v[198:199], v[146:147]
	v_pk_add_f32 v[50:51], v[180:181], v[148:149]
	v_pk_add_f32 v[52:53], v[182:183], v[150:151]
	v_pk_add_f32 v[54:55], v[184:185], v[152:153]
	v_pk_add_f32 v[56:57], v[186:187], v[154:155]
	v_pk_add_f32 v[58:59], v[188:189], v[156:157]
	v_pk_add_f32 v[60:61], v[190:191], v[158:159]
	v_pk_add_f32 v[40:41], v[196:197], v[160:161]
	v_pk_add_f32 v[42:43], v[198:199], v[162:163]
	s_mov_b32 s86, 0x800000
	s_mov_b64 s[0:1], 0
	s_nop 1

; DI void rowpass(const Params& p, bool init, float scale, const float* __restrict__ gpost, const float* __restrict__ gnext, int nparts, int bid, int nb, const int tid) {
;     ...
;                 for (int pt = 0; pt < nparts; ++pt) {
; #pragma unroll
;                     for (int i = 0; i < 4; ++i) { const float4 u = *(const float4*)(YS + (size_t)pt * NS * DM + (size_t)(row - NP) * DM + i * 256 + lane * 4); y[i].x += u.x; y[i].y += u.y; y[i].z += u.z; y[i].w += u.w; }
;                 }
.LBB0_230:
	flat_load_dwordx4 v[36:39], v[56:57]
	flat_load_dwordx4 v[32:35], v[56:57] offset:1024
	flat_load_dwordx4 v[28:31], v[56:57] offset:2048
	flat_load_dwordx4 v[24:27], v[56:57] offset:3072
	s_cmpk_lt_i32 s2, 0x4000
	s_mov_b64 s[0:1], -1
	s_cbranch_scc1 .LBB0_232
	s_add_i32 s86, s2, 0xffffc000
	s_lshl_b64 s[0:1], s[86:87], 12
	v_lshl_add_u64 v[42:43], v[18:19], 0, s[0:1]
	global_load_dwordx4 v[96:99], v[42:43], off
	global_load_dwordx4 v[100:103], v[42:43], off offset:1024
	global_load_dwordx4 v[104:107], v[42:43], off offset:2048
	global_load_dwordx4 v[108:111], v[42:43], off offset:3072
	v_add_co_u32_e32 v176, vcc, 0x100000, v42
	s_nop 1
	v_addc_co_u32_e32 v177, vcc, 0, v43, vcc
	global_load_dwordx4 v[112:115], v[176:177], off
	global_load_dwordx4 v[116:119], v[176:177], off offset:1024
	global_load_dwordx4 v[120:123], v[176:177], off offset:2048
	global_load_dwordx4 v[124:127], v[176:177], off offset:3072
	v_add_co_u32_e32 v176, vcc, 0x200000, v42
	s_nop 1
	v_addc_co_u32_e32 v177, vcc, 0, v43, vcc
	global_load_dwordx4 v[128:131], v[176:177], off
	global_load_dwordx4 v[132:135], v[176:177], off offset:1024
	global_load_dwordx4 v[136:139], v[176:177], off offset:2048
	global_load_dwordx4 v[140:143], v[176:177], off offset:3072
	v_add_co_u32_e32 v176, vcc, 0x300000, v42
	s_nop 1
	v_addc_co_u32_e32 v177, vcc, 0, v43, vcc
	global_load_dwordx4 v[144:147], v[176:177], off
	global_load_dwordx4 v[148:151], v[176:177], off offset:1024
	global_load_dwordx4 v[152:155], v[176:177], off offset:2048
	global_load_dwordx4 v[156:159], v[176:177], off offset:3072
	s_waitcnt vmcnt(0) lgkmcnt(0)
	v_pk_add_f32 v[160:161], v[96:97], 0 op_sel_hi:[1,0]
	v_pk_add_f32 v[162:163], v[98:99], 0 op_sel_hi:[1,0]
	v_pk_add_f32 v[164:165], v[100:101], 0 op_sel_hi:[1,0]
	v_pk_add_f32 v[166:167], v[102:103], 0 op_sel_hi:[1,0]
	v_pk_add_f32 v[168:169], v[104:105], 0 op_sel_hi:[1,0]
	v_pk_add_f32 v[170:171], v[106:107], 0 op_sel_hi:[1,0]
	v_pk_add_f32 v[172:173], v[108:109], 0 op_sel_hi:[1,0]
	v_pk_add_f32 v[174:175], v[110:111], 0 op_sel_hi:[1,0]
	v_pk_add_f32 v[160:161], v[160:161], v[112:113]
	v_pk_add_f32 v[162:163], v[162:163], v[114:115]
	v_pk_add_f32 v[164:165], v[164:165], v[116:117]
	v_pk_add_f32 v[166:167], v[166:167], v[118:119]
	v_pk_add_f32 v[168:169], v[168:169], v[120:121]
	v_pk_add_f32 v[170:171], v[170:171], v[122:123]
	v_pk_add_f32 v[172:173], v[172:173], v[124:125]
	v_pk_add_f32 v[174:175], v[174:175], v[126:127]
	v_pk_add_f32 v[160:161], v[160:161], v[128:129]
	v_pk_add_f32 v[162:163], v[162:163], v[130:131]
	v_pk_add_f32 v[164:165], v[164:165], v[132:133]
	v_pk_add_f32 v[166:167], v[166:167], v[134:135]
	v_pk_add_f32 v[168:169], v[168:169], v[136:137]
	v_pk_add_f32 v[170:171], v[170:171], v[138:139]
	v_pk_add_f32 v[172:173], v[172:173], v[140:141]
	v_pk_add_f32 v[174:175], v[174:175], v[142:143]
	v_pk_add_f32 v[160:161], v[160:161], v[144:145]
	v_pk_add_f32 v[162:163], v[162:163], v[146:147]
	v_pk_add_f32 v[164:165], v[164:165], v[148:149]
	v_pk_add_f32 v[166:167], v[166:167], v[150:151]
	v_pk_add_f32 v[168:169], v[168:169], v[152:153]
	v_pk_add_f32 v[170:171], v[170:171], v[154:155]
	v_pk_add_f32 v[172:173], v[172:173], v[156:157]
	v_pk_add_f32 v[174:175], v[174:175], v[158:159]
	v_add_co_u32_e32 v176, vcc, 0x400000, v42
	s_nop 1
	v_addc_co_u32_e32 v177, vcc, 0, v43, vcc
	global_load_dwordx4 v[96:99], v[176:177], off
	global_load_dwordx4 v[100:103], v[176:177], off offset:1024
	global_load_dwordx4 v[104:107], v[176:177], off offset:2048
	global_load_dwordx4 v[108:111], v[176:177], off offset:3072
	v_add_co_u32_e32 v176, vcc, 0x500000, v42
	s_nop 1
	v_addc_co_u32_e32 v177, vcc, 0, v43, vcc
	global_load_dwordx4 v[112:115], v[176:177], off
	global_load_dwordx4 v[116:119], v[176:177], off offset:1024
	global_load_dwordx4 v[120:123], v[176:177], off offset:2048
	global_load_dwordx4 v[124:127], v[176:177], off offset:3072
	v_add_co_u32_e32 v176, vcc, 0x600000, v42
	s_nop 1
	v_addc_co_u32_e32 v177, vcc, 0, v43, vcc
	global_load_dwordx4 v[128:131], v[176:177], off
	global_load_dwordx4 v[132:135], v[176:177], off offset:1024
	global_load_dwordx4 v[136:139], v[176:177], off offset:2048
	global_load_dwordx4 v[140:143], v[176:177], off offset:3072
	v_add_co_u32_e32 v176, vcc, 0x700000, v42
	s_nop 1
	v_addc_co_u32_e32 v177, vcc, 0, v43, vcc
	global_load_dwordx4 v[144:147], v[176:177], off
	global_load_dwordx4 v[148:151], v[176:177], off offset:1024
	global_load_dwordx4 v[152:155], v[176:177], off offset:2048
	global_load_dwordx4 v[156:159], v[176:177], off offset:3072
	s_waitcnt vmcnt(0) lgkmcnt(0)
	v_pk_add_f32 v[160:161], v[160:161], v[96:97]
	v_pk_add_f32 v[162:163], v[162:163], v[98:99]
	v_pk_add_f32 v[164:165], v[164:165], v[100:101]
	v_pk_add_f32 v[166:167], v[166:167], v[102:103]
	v_pk_add_f32 v[168:169], v[168:169], v[104:105]
	v_pk_add_f32 v[170:171], v[170:171], v[106:107]
	v_pk_add_f32 v[172:173], v[172:173], v[108:109]
	v_pk_add_f32 v[174:175], v[174:175], v[110:111]
	v_pk_add_f32 v[160:161], v[160:161], v[112:113]
	v_pk_add_f32 v[162:163], v[162:163], v[114:115]
	v_pk_add_f32 v[164:165], v[164:165], v[116:117]
	v_pk_add_f32 v[166:167], v[166:167], v[118:119]
	v_pk_add_f32 v[168:169], v[168:169], v[120:121]
	v_pk_add_f32 v[170:171], v[170:171], v[122:123]
	v_pk_add_f32 v[172:173], v[172:173], v[124:125]
	v_pk_add_f32 v[174:175], v[174:175], v[126:127]
	v_pk_add_f32 v[160:161], v[160:161], v[128:129]
	v_pk_add_f32 v[162:163], v[162:163], v[130:131]
	v_pk_add_f32 v[164:165], v[164:165], v[132:133]
	v_pk_add_f32 v[166:167], v[166:167], v[134:135]
	v_pk_add_f32 v[168:169], v[168:169], v[136:137]
	v_pk_add_f32 v[170:171], v[170:171], v[138:139]
	v_pk_add_f32 v[172:173], v[172:173], v[140:141]
	v_pk_add_f32 v[174:175], v[174:175], v[142:143]
	v_pk_add_f32 v[58:59], v[160:161], v[144:145]
	v_pk_add_f32 v[60:61], v[162:163], v[146:147]
	v_pk_add_f32 v[62:63], v[164:165], v[148:149]
	v_pk_add_f32 v[64:65], v[166:167], v[150:151]
	v_pk_add_f32 v[68:69], v[168:169], v[152:153]
	v_pk_add_f32 v[70:71], v[170:171], v[154:155]
	v_pk_add_f32 v[40:41], v[172:173], v[156:157]
	v_pk_add_f32 v[42:43], v[174:175], v[158:159]
	s_mov_b32 s86, 0x800000
	s_mov_b64 s[0:1], 0
	s_nop 1
